# rowpass k6/k9: late gp chunks and all gn chunks loaded once per phase before the row loop (2 serialized L2 round trips per row removed)
# speedup vs baseline: 1.0016x; 1.0016x over previous
;     __device__ __forceinline__ const float* in(int i) const { return (const float*)(const __attribute__((address_space(1))) float*)get(i); }
;     __device__ __forceinline__ float* out() const { return (float*)(__attribute__((address_space(1))) float*)get(21); }
; __device__ __forceinline__ void rowpass_row(const float* xi, const bf16* y, const float* gp, const float* gn, float* xo, bf16* h, int lane) {
;     ...
;     if (gn) {
;         const f32x4* gnr = (const f32x4*)gn + lane;
; #pragma unroll
;         for (int j = 0; j < 8; ++j) gv[j] = gnr[64 * j];
; __global__ void __launch_bounds__(512, 2) mega_fwd(Args ka) {
;     ...
;             else if (k == 9) { float* xo = a.out(); const float* gn = (l + 1 < DEPTH) ? a.in(15) + (size_t)(l + 1) * DM : nullptr;
;                 for (int m = gw; m < M; m += ngw) rowpass_row(xo + (size_t)m * DM, (const bf16*)(ws + WS_Y) + (size_t)m * DM, a.in(18) + (size_t)l * DM, gn, xo + (size_t)m * DM, H + (size_t)m * DM, lane); }
.LBB0_85:
	s_cmpk_gt_i32 s4, 0x1fff
	s_cbranch_scc1 .LBB0_90
	s_lshl_b64 s[8:9], s[30:31], 13
	v_lshlrev_b32_e32 v0, 4, v148
	s_cmp_lg_u64 s[0:1], 0
	v_lshl_add_u64 v[58:59], s[0:1], 0, v[0:1]
	s_mov_b64 s[0:1], 0x1000
	v_lshl_add_u64 v[60:61], v[58:59], 0, s[0:1]
	s_mov_b64 s[0:1], 0x1400
	s_cselect_b64 s[10:11], -1, 0
	v_lshl_add_u64 v[62:63], v[58:59], 0, s[0:1]
	s_mov_b64 s[0:1], 0x1800
	s_ashr_i32 s5, s4, 31
	v_lshl_add_u64 v[64:65], v[58:59], 0, s[0:1]
	s_lshl_b64 s[0:1], s[4:5], 12
	s_add_u32 s0, s37, s0
	v_lshlrev_b32_e32 v2, 3, v148
	v_mov_b32_e32 v3, v1
	s_addc_u32 s1, s36, s1
	v_lshl_add_u64 v[2:3], s[0:1], 0, v[2:3]
	s_mov_b64 s[0:1], 0x2e000e00
	s_ashr_i32 s7, s6, 31
	s_waitcnt vmcnt(0)
	v_lshl_add_u64 v[68:69], v[2:3], 0, s[0:1]
	s_lshl_b64 s[12:13], s[6:7], 12
	s_lshl_b64 s[0:1], s[4:5], 13
	s_add_u32 s0, s15, s0
	s_addc_u32 s1, s14, s1
	s_mov_b64 s[16:17], 0x1c00
	v_lshl_add_u64 v[2:3], s[0:1], 0, v[0:1]
	v_lshl_add_u64 v[66:67], v[58:59], 0, s[16:17]
	v_lshl_add_u64 v[70:71], v[2:3], 0, s[16:17]
	s_lshl_b64 s[14:15], s[6:7], 13
	v_lshlrev_b32_e32 v0, 4, v148
	s_mov_b32 s5, s4
	v_mov_b32_e32 v2, s73
	ds_read_b64 v[34:35], v2 offset:144
	s_waitcnt lgkmcnt(0)
	v_readfirstlane_b32 s0, v34
	v_readfirstlane_b32 s1, v35
	s_add_u32 s0, s0, s8
	s_addc_u32 s1, s1, s9
	global_load_dwordx4 v[126:129], v0, s[0:1] offset:1024
	global_load_dwordx4 v[130:133], v0, s[0:1]
	s_andn2_b64 vcc, exec, s[10:11]
	s_cbranch_vccnz .Lrp9_nogn
	global_load_dwordx4 v[150:153], v[58:59], off
	global_load_dwordx4 v[154:157], v[58:59], off offset:1024
	global_load_dwordx4 v[158:161], v[58:59], off offset:2048
	global_load_dwordx4 v[162:165], v[58:59], off offset:3072
	global_load_dwordx4 v[166:169], v[60:61], off
	global_load_dwordx4 v[170:173], v[62:63], off
	global_load_dwordx4 v[174:177], v[64:65], off
	global_load_dwordx4 v[178:181], v[66:67], off
.Lrp9_nogn:
	s_branch .LBB0_88

; __device__ __forceinline__ float bf_lo(unsigned w) { return __uint_as_float(w << 16); }
; __device__ __forceinline__ float bf_hi(unsigned w) { return __uint_as_float(w & 0xffff0000u); }
; __device__ __forceinline__ void rowpass_row(const float* xi, const bf16* y, const float* gp, const float* gn, float* xo, bf16* h, int lane) {
;     const u32x2* yr = (const u32x2*)y + lane; const f32x4* xr = (const f32x4*)xi + lane; const f32x4* gpr = (const f32x4*)gp + lane;
;     u32x2 yw[8]; f32x4 xv[8], gv[8];
; #pragma unroll
;     for (int j = 0; j < 8; ++j) { yw[j] = yr[64 * j]; xv[j] = xr[64 * j]; gv[j] = gpr[64 * j]; }
;     asm volatile("" : "+v"(xv[0]), "+v"(xv[1]), "+v"(xv[2]), "+v"(xv[3]), "+v"(xv[4]), "+v"(xv[5]), "+v"(xv[6]), "+v"(xv[7]));
;     asm volatile("" : "+v"(gv[0]), "+v"(gv[1]), "+v"(gv[2]), "+v"(gv[3]), "+v"(gv[4]), "+v"(gv[5]), "+v"(gv[6]), "+v"(gv[7]));
;     f32x4 v[8]; float s = 0.f;
; #pragma unroll
;     for (int j = 0; j < 8; ++j) { const u32x2 w = yw[j]; v[j].x = bf_lo(w.x); v[j].y = bf_hi(w.x); v[j].z = bf_lo(w.y); v[j].w = bf_hi(w.y); s += (v[j].x * v[j].x + v[j].y * v[j].y) + (v[j].z * v[j].z + v[j].w * v[j].w); }
;     const float r = 1.0f / sqrtf(wave_sum(s) * (1.0f / DM) + 1e-6f);
.LBB0_88:
	global_load_dwordx2 v[74:75], v[68:69], off offset:-3584
	global_load_dwordx2 v[76:77], v[68:69], off offset:-3072
	global_load_dwordx2 v[78:79], v[68:69], off offset:-2560
	global_load_dwordx2 v[80:81], v[68:69], off offset:-2048
	global_load_dwordx2 v[82:83], v[68:69], off offset:-1536
	global_load_dwordx2 v[84:85], v[68:69], off offset:-1024
	global_load_dwordx2 v[86:87], v[68:69], off offset:-512
	global_load_dwordx2 v[88:89], v[68:69], off
	v_mov_b32_e32 v2, s73
	global_load_dwordx4 v[30:33], v[70:71], off
	global_load_dwordx4 v[26:29], v[70:71], off offset:-1024
	global_load_dwordx4 v[22:25], v[70:71], off offset:-2048
	ds_read_b64 v[34:35], v2 offset:144
	s_movk_i32 s0, 0xf000
	v_add_co_u32_e32 v72, vcc, s0, v70
	s_waitcnt lgkmcnt(0)
	v_readfirstlane_b32 s0, v34
	v_readfirstlane_b32 s1, v35
	s_add_u32 s0, s0, s8
	s_addc_u32 s1, s1, s9
	v_addc_co_u32_e32 v73, vcc, -1, v71, vcc
	v_lshl_add_u64 v[34:35], s[0:1], 0, v[0:1]
	v_add_co_u32_e32 v46, vcc, s70, v34
	global_load_dwordx4 v[18:21], v[70:71], off offset:-3072
	global_load_dwordx4 v[14:17], v[70:71], off offset:-4096
	global_load_dwordx4 v[10:13], v[72:73], off offset:-1024
	global_load_dwordx4 v[2:5], v[72:73], off offset:-2048
	global_load_dwordx4 v[6:9], v[72:73], off offset:-3072
	v_addc_co_u32_e32 v47, vcc, 0, v35, vcc
	global_load_dwordx4 v[50:53], v0, s[0:1] offset:3072
	global_load_dwordx4 v[54:57], v0, s[0:1] offset:2048
	global_load_dwordx4 v[34:37], v[46:47], off offset:3072
	global_load_dwordx4 v[38:41], v[46:47], off offset:2048
	global_load_dwordx4 v[42:45], v[46:47], off offset:1024
	s_nop 0
	global_load_dwordx4 v[46:49], v[46:47], off
	s_waitcnt vmcnt(0)
	v_and_b32_e32 v91, 0xffff0000, v74
	v_and_b32_e32 v93, 0xffff0000, v75
	v_lshlrev_b32_e32 v90, 16, v74
	v_lshlrev_b32_e32 v103, 16, v80
	v_lshlrev_b32_e32 v92, 16, v75
	v_and_b32_e32 v97, 0xffff0000, v77
	v_and_b32_e32 v96, 0xffff0000, v76
	v_lshlrev_b32_e32 v98, 16, v78
	v_and_b32_e32 v99, 0xffff0000, v78
	v_mul_f32_e32 v74, v93, v93
	v_mul_f32_e32 v78, v91, v91
	v_mov_b32_e32 v75, v103
	v_lshlrev_b32_e32 v95, 16, v77
	v_lshlrev_b32_e32 v94, 16, v76
	v_lshlrev_b32_e32 v100, 16, v79
	v_and_b32_e32 v101, 0xffff0000, v79
	v_pk_mul_f32 v[76:77], v[96:97], v[96:97]
	v_pk_fma_f32 v[116:117], v[92:93], v[92:93], v[74:75] op_sel_hi:[1,1,0]
	v_pk_fma_f32 v[78:79], v[90:91], v[90:91], v[78:79] op_sel_hi:[1,1,0]
	v_and_b32_e32 v105, 0xffff0000, v80
	v_lshlrev_b32_e32 v106, 16, v81
	v_and_b32_e32 v107, 0xffff0000, v81
	v_lshlrev_b32_e32 v108, 16, v82
	v_and_b32_e32 v110, 0xffff0000, v82
	v_mul_f32_e32 v80, v99, v99
	v_mul_f32_e32 v82, v101, v101
	v_pk_fma_f32 v[76:77], v[94:95], v[94:95], v[76:77]
	v_mov_b32_e32 v102, v78
	v_mov_b32_e32 v74, v116
	v_lshlrev_b32_e32 v109, 16, v83
	v_and_b32_e32 v111, 0xffff0000, v83
	v_mul_f32_e32 v104, v105, v105
	v_mul_f32_e32 v118, v106, v106
	v_mul_f32_e32 v119, v107, v107
	v_pk_fma_f32 v[80:81], v[98:99], v[98:99], v[80:81] op_sel_hi:[1,1,0]
	v_pk_fma_f32 v[82:83], v[100:101], v[100:101], v[82:83] op_sel_hi:[1,1,0]
	v_pk_add_f32 v[78:79], v[78:79], v[116:117]
	v_pk_add_f32 v[76:77], v[76:77], v[76:77] op_sel:[0,1] op_sel_hi:[1,0]
	v_pk_mul_f32 v[74:75], v[102:103], v[74:75]
	v_mov_b32_e32 v81, v118
	v_mov_b32_e32 v83, v119
	v_mov_b32_e32 v77, v104
	v_mov_b32_e32 v79, v75
	v_pk_mul_f32 v[114:115], v[110:111], v[110:111]
	v_pk_add_f32 v[80:81], v[80:81], v[82:83]
	v_pk_add_f32 v[74:75], v[78:79], v[76:77]
	v_pk_fma_f32 v[114:115], v[108:109], v[108:109], v[114:115]
	v_pk_add_f32 v[74:75], v[74:75], v[80:81]
	v_and_b32_e32 v117, 0xffff0000, v85
	v_and_b32_e32 v116, 0xffff0000, v84
	v_lshlrev_b32_e32 v113, 16, v85
	v_lshlrev_b32_e32 v112, 16, v84
	v_pk_add_f32 v[114:115], v[114:115], v[114:115] op_sel:[0,1] op_sel_hi:[1,0]
	v_pk_mul_f32 v[76:77], v[116:117], v[116:117]
	v_lshlrev_b32_e32 v123, 16, v88
	v_pk_add_f32 v[74:75], v[74:75], v[74:75] op_sel:[0,1] op_sel_hi:[1,0]
	v_pk_fma_f32 v[76:77], v[112:113], v[112:113], v[76:77]
	v_and_b32_e32 v125, 0xffff0000, v88
	v_mov_b32_e32 v122, v74
	v_mov_b32_e32 v78, v114
	v_mov_b32_e32 v79, v123
	v_mul_f32_e32 v80, v125, v125
	v_pk_add_f32 v[74:75], v[74:75], v[114:115]
	v_pk_mul_f32 v[78:79], v[122:123], v[78:79]
	v_pk_add_f32 v[76:77], v[76:77], v[76:77] op_sel:[0,1] op_sel_hi:[1,0]
	v_and_b32_e32 v119, 0xffff0000, v86
	v_and_b32_e32 v121, 0xffff0000, v87
	v_mov_b32_e32 v75, v79
	v_mov_b32_e32 v77, v80
	v_lshlrev_b32_e32 v118, 16, v86
	v_lshlrev_b32_e32 v120, 16, v87
	v_lshlrev_b32_e32 v88, 16, v89
	v_and_b32_e32 v89, 0xffff0000, v89
	v_pk_add_f32 v[74:75], v[74:75], v[76:77]
	v_mul_f32_e32 v76, v119, v119
	v_mul_f32_e32 v78, v121, v121
	v_mul_f32_e32 v81, v88, v88
	v_mul_f32_e32 v82, v89, v89
	v_pk_fma_f32 v[76:77], v[118:119], v[118:119], v[76:77] op_sel_hi:[1,1,0]
	v_pk_fma_f32 v[78:79], v[120:121], v[120:121], v[78:79] op_sel_hi:[1,1,0]
	v_mov_b32_e32 v77, v81
	v_mov_b32_e32 v79, v82
	v_pk_add_f32 v[76:77], v[76:77], v[78:79]
	v_mov_b64 v[80:81], v[126:127]
	v_mov_b64 v[82:83], v[128:129]
	v_mov_b64 v[84:85], v[130:131]
	v_mov_b64 v[86:87], v[132:133]
	v_pk_add_f32 v[74:75], v[74:75], v[76:77]
	v_add_f32_e32 v75, v74, v75
	v_and_b32_e32 v74, 64, v220
	v_add_u32_e32 v79, 64, v74
	v_xor_b32_e32 v74, 32, v220
	v_cmp_lt_i32_e32 vcc, v74, v79
	s_nop 1
	v_cndmask_b32_e32 v74, v220, v74, vcc
	v_lshlrev_b32_e32 v74, 2, v74
	ds_bpermute_b32 v76, v74, v75
	s_waitcnt lgkmcnt(0)
	v_add_f32_e32 v76, v75, v76
	v_xor_b32_e32 v75, 16, v220
	v_cmp_lt_i32_e32 vcc, v75, v79
	s_nop 1
	v_cndmask_b32_e32 v75, v220, v75, vcc
	v_lshlrev_b32_e32 v75, 2, v75
	ds_bpermute_b32 v77, v75, v76
	s_waitcnt lgkmcnt(0)
; __device__ __forceinline__ void rowpass_row(const float* xi, const bf16* y, const float* gp, const float* gn, float* xo, bf16* h, int lane) {
;     ...
;     const float r = 1.0f / sqrtf(wave_sum(s) * (1.0f / DM) + 1e-6f);
;     float s2 = 0.f;
; #pragma unroll
;     for (int j = 0; j < 8; ++j) { v[j] = xv[j] + v[j] * r * gv[j]; s2 += (v[j].x * v[j].x + v[j].y * v[j].y) + (v[j].z * v[j].z + v[j].w * v[j].w); }
;     f32x4* xw = (f32x4*)xo + lane;
; #pragma unroll
;     for (int j = 0; j < 8; ++j) xw[64 * j] = v[j];
	v_add_f32_e32 v77, v76, v77
	v_xor_b32_e32 v76, 8, v220
	v_cmp_lt_i32_e32 vcc, v76, v79
	s_nop 1
	v_cndmask_b32_e32 v76, v220, v76, vcc
	v_lshlrev_b32_e32 v76, 2, v76
	ds_bpermute_b32 v78, v76, v77
	s_waitcnt lgkmcnt(0)
	v_add_f32_e32 v78, v77, v78
	v_xor_b32_e32 v77, 4, v220
	v_cmp_lt_i32_e32 vcc, v77, v79
	s_nop 1
	v_cndmask_b32_e32 v77, v220, v77, vcc
	v_lshlrev_b32_e32 v77, 2, v77
	ds_bpermute_b32 v102, v77, v78
	s_waitcnt lgkmcnt(0)
	v_add_f32_e32 v102, v78, v102
	v_xor_b32_e32 v78, 2, v220
	v_cmp_lt_i32_e32 vcc, v78, v79
	s_nop 1
	v_cndmask_b32_e32 v78, v220, v78, vcc
	v_lshlrev_b32_e32 v78, 2, v78
	ds_bpermute_b32 v104, v78, v102
	s_waitcnt lgkmcnt(0)
	v_add_f32_e32 v102, v102, v104
	v_xor_b32_e32 v104, 1, v220
	v_cmp_lt_i32_e32 vcc, v104, v79
	s_nop 1
	v_cndmask_b32_e32 v79, v220, v104, vcc
	v_lshlrev_b32_e32 v79, 2, v79
	ds_bpermute_b32 v104, v79, v102
	s_waitcnt lgkmcnt(0)
	v_add_f32_e32 v102, v102, v104
	v_fmamk_f32 v102, v102, 0x3a000000, v221
	v_mul_f32_e32 v104, 0x4f800000, v102
	v_cmp_gt_f32_e32 vcc, s87, v102
	s_nop 1
	v_cndmask_b32_e32 v102, v102, v104, vcc
	v_sqrt_f32_e32 v104, v102
	s_nop 0
	v_add_u32_e32 v114, -1, v104
	v_fma_f32 v115, -v114, v104, v102
	v_cmp_ge_f32_e64 s[0:1], 0, v115
	v_add_u32_e32 v115, 1, v104
	s_nop 0
	v_cndmask_b32_e64 v114, v104, v114, s[0:1]
	v_fma_f32 v104, -v115, v104, v102
	v_cmp_lt_f32_e64 s[0:1], 0, v104
	s_nop 1
	v_cndmask_b32_e64 v104, v114, v115, s[0:1]
	v_mul_f32_e32 v114, 0x37800000, v104
	v_cndmask_b32_e32 v104, v104, v114, vcc
	v_cmp_class_f32_e32 vcc, v102, v222
	s_nop 1
	v_cndmask_b32_e32 v102, v104, v102, vcc
	v_div_scale_f32 v104, s[0:1], v102, v102, 1.0
	v_rcp_f32_e32 v114, v104
	s_nop 0
	v_fma_f32 v115, -v104, v114, 1.0
	v_fmac_f32_e32 v114, v115, v114
	v_div_scale_f32 v115, vcc, 1.0, v102, 1.0
	v_mul_f32_e32 v122, v115, v114
	v_fma_f32 v124, -v104, v122, v115
	v_fmac_f32_e32 v122, v124, v114
	v_fma_f32 v104, -v104, v122, v115
	v_div_fmas_f32 v104, v104, v114, v122
	v_div_fixup_f32 v102, v104, v102, 1.0
	v_pk_mul_f32 v[90:91], v[102:103], v[90:91] op_sel_hi:[0,1]
	v_pk_fma_f32 v[6:7], v[84:85], v[90:91], v[6:7]
	v_mov_b32_e32 v84, v94
	v_mov_b32_e32 v85, v96
	v_pk_mul_f32 v[84:85], v[102:103], v[84:85] op_sel_hi:[0,1]
	v_pk_mul_f32 v[92:93], v[102:103], v[92:93] op_sel_hi:[0,1]
	v_mov_b32_e32 v96, v95
	v_pk_fma_f32 v[2:3], v[80:81], v[84:85], v[2:3]
	v_pk_mul_f32 v[80:81], v[102:103], v[98:99] op_sel_hi:[0,1]
	v_mov_b32_e32 v104, v103
	v_pk_fma_f32 v[8:9], v[86:87], v[92:93], v[8:9]
	v_pk_mul_f32 v[86:87], v[102:103], v[96:97] op_sel_hi:[0,1]
	v_pk_fma_f32 v[10:11], v[54:55], v[80:81], v[10:11]
	v_pk_mul_f32 v[54:55], v[104:105], v[102:103] op_sel_hi:[1,0]
	v_pk_fma_f32 v[4:5], v[82:83], v[86:87], v[4:5]
	v_pk_mul_f32 v[82:83], v[102:103], v[100:101] op_sel_hi:[0,1]
	v_pk_fma_f32 v[14:15], v[50:51], v[54:55], v[14:15]
	v_mov_b32_e32 v50, v108
	v_mov_b32_e32 v51, v110
	v_pk_fma_f32 v[12:13], v[56:57], v[82:83], v[12:13]
	v_pk_mul_f32 v[56:57], v[106:107], v[102:103] op_sel_hi:[1,0]
	v_pk_mul_f32 v[50:51], v[102:103], v[50:51] op_sel_hi:[0,1]
	v_mov_b32_e32 v110, v109
	v_pk_fma_f32 v[16:17], v[52:53], v[56:57], v[16:17]
	v_pk_mul_f32 v[52:53], v[102:103], v[110:111] op_sel_hi:[0,1]
	v_pk_fma_f32 v[18:19], v[46:47], v[50:51], v[18:19]
	v_mov_b32_e32 v46, v112
	v_mov_b32_e32 v47, v116
	v_mov_b32_e32 v116, v113
	v_pk_fma_f32 v[20:21], v[48:49], v[52:53], v[20:21]
	v_pk_mul_f32 v[46:47], v[102:103], v[46:47] op_sel_hi:[0,1]
	v_pk_mul_f32 v[48:49], v[102:103], v[116:117] op_sel_hi:[0,1]
	v_pk_fma_f32 v[24:25], v[44:45], v[48:49], v[24:25]
	v_pk_fma_f32 v[22:23], v[42:43], v[46:47], v[22:23]
	v_pk_mul_f32 v[42:43], v[102:103], v[118:119] op_sel_hi:[0,1]
	v_pk_mul_f32 v[44:45], v[102:103], v[120:121] op_sel_hi:[0,1]
	v_mov_b32_e32 v124, v123
	v_pk_fma_f32 v[28:29], v[40:41], v[44:45], v[28:29]
	v_pk_fma_f32 v[26:27], v[38:39], v[42:43], v[26:27]
	v_pk_mul_f32 v[38:39], v[124:125], v[102:103] op_sel_hi:[1,0]
	v_pk_mul_f32 v[40:41], v[88:89], v[102:103] op_sel_hi:[1,0]
	v_pk_fma_f32 v[30:31], v[34:35], v[38:39], v[30:31]
	v_pk_fma_f32 v[32:33], v[36:37], v[40:41], v[32:33]
	s_andn2_b64 vcc, exec, s[10:11]
	global_store_dwordx4 v[72:73], v[6:9], off offset:-3072
	global_store_dwordx4 v[72:73], v[2:5], off offset:-2048
	global_store_dwordx4 v[72:73], v[10:13], off offset:-1024
	global_store_dwordx4 v[70:71], v[14:17], off offset:-4096
	global_store_dwordx4 v[70:71], v[18:21], off offset:-3072
	global_store_dwordx4 v[70:71], v[22:25], off offset:-2048
	global_store_dwordx4 v[70:71], v[26:29], off offset:-1024
	global_store_dwordx4 v[70:71], v[30:33], off
	s_cbranch_vccnz .LBB0_87
; __device__ __forceinline__ unsigned pkh(float lo, float hi) { f32v2_t v; v.x = lo; v.y = hi; return __builtin_bit_cast(unsigned, __builtin_convertvector(v, bf16v2_t)); }
; __device__ __forceinline__ void rowpass_row(const float* xi, const bf16* y, const float* gp, const float* gn, float* xo, bf16* h, int lane) {
;     ...
;     for (int j = 0; j < 8; ++j) { v[j] = xv[j] + v[j] * r * gv[j]; s2 += (v[j].x * v[j].x + v[j].y * v[j].y) + (v[j].z * v[j].z + v[j].w * v[j].w); }
;     f32x4* xw = (f32x4*)xo + lane;
; #pragma unroll
;     for (int j = 0; j < 8; ++j) xw[64 * j] = v[j];
;     if (gn) {
;         const f32x4* gnr = (const f32x4*)gn + lane;
; #pragma unroll
;         for (int j = 0; j < 8; ++j) gv[j] = gnr[64 * j];
;         asm volatile("" : "+v"(gv[0]), "+v"(gv[1]), "+v"(gv[2]), "+v"(gv[3]), "+v"(gv[4]), "+v"(gv[5]), "+v"(gv[6]), "+v"(gv[7]));
;         const float r2 = 1.0f / sqrtf(wave_sum(s2) * (1.0f / DM) + 1e-6f);
;         u32x2* o8 = (u32x2*)h + lane;
; #pragma unroll
;         for (int j = 0; j < 8; ++j) { const f32x4 g = gv[j]; u32x2 w; w.x = pkh(v[j].x * r2 * g.x, v[j].y * r2 * g.y); w.y = pkh(v[j].z * r2 * g.z, v[j].w * r2 * g.w); o8[64 * j] = w; }
	v_mov_b32_e32 v36, v7
	v_mov_b32_e32 v37, v3
	v_mov_b32_e32 v34, v6
	v_mov_b32_e32 v35, v2
	v_pk_mul_f32 v[36:37], v[36:37], v[36:37]
	v_mov_b32_e32 v38, v9
	v_mov_b32_e32 v39, v5
	v_pk_fma_f32 v[34:35], v[34:35], v[34:35], v[36:37]
	v_mov_b32_e32 v36, v8
	v_mov_b32_e32 v37, v4
	v_pk_mul_f32 v[38:39], v[38:39], v[38:39]
	s_nop 0
	v_pk_fma_f32 v[36:37], v[36:37], v[36:37], v[38:39]
	v_pk_mul_f32 v[38:39], v[10:11], v[10:11]
	v_pk_add_f32 v[34:35], v[34:35], v[36:37]
	v_pk_mul_f32 v[36:37], v[12:13], v[12:13]
	v_pk_add_f32 v[34:35], v[34:35], v[34:35] op_sel_hi:[0,1]
	v_pk_mov_b32 v[40:41], v[38:39], v[36:37] op_sel:[1,0]
	v_mov_b32_e32 v39, v37
	v_mul_f32_e32 v34, v14, v14
	v_pk_add_f32 v[36:37], v[40:41], v[38:39]
	v_pk_fma_f32 v[38:39], v[14:15], v[14:15], v[34:35] op_sel_hi:[1,1,0]
	v_mul_f32_e32 v34, v16, v16
	v_pk_add_f32 v[36:37], v[36:37], v[36:37] op_sel_hi:[0,1]
	v_pk_fma_f32 v[40:41], v[16:17], v[16:17], v[34:35] op_sel_hi:[1,1,0]
	v_mul_f32_e32 v38, v18, v18
	v_mul_f32_e32 v40, v19, v19
	v_mul_f32_e32 v36, v20, v20
	v_mul_f32_e32 v34, v21, v21
	v_pk_add_f32 v[38:39], v[38:39], v[40:41]
	v_pk_add_f32 v[34:35], v[36:37], v[34:35]
	v_pk_mul_f32 v[36:37], v[24:25], v[24:25]
	v_pk_add_f32 v[34:35], v[38:39], v[34:35]
	v_pk_mul_f32 v[38:39], v[22:23], v[22:23]
	v_pk_add_f32 v[34:35], v[34:35], v[34:35] op_sel_hi:[0,1]
	v_pk_mov_b32 v[40:41], v[38:39], v[36:37] op_sel:[1,0]
	v_mov_b32_e32 v39, v37
	v_mul_f32_e32 v34, v26, v26
	v_pk_add_f32 v[36:37], v[40:41], v[38:39]
	v_pk_fma_f32 v[38:39], v[26:27], v[26:27], v[34:35] op_sel_hi:[1,1,0]
	v_mul_f32_e32 v34, v28, v28
	v_pk_add_f32 v[36:37], v[36:37], v[36:37] op_sel_hi:[0,1]
	v_pk_fma_f32 v[40:41], v[28:29], v[28:29], v[34:35] op_sel_hi:[1,1,0]
	v_mul_f32_e32 v38, v30, v30
	v_mul_f32_e32 v40, v31, v31
	v_mul_f32_e32 v36, v32, v32
	v_mul_f32_e32 v34, v33, v33
	v_pk_add_f32 v[38:39], v[38:39], v[40:41]
	v_pk_add_f32 v[34:35], v[36:37], v[34:35]
	s_nop 0
	v_pk_add_f32 v[34:35], v[38:39], v[34:35]
	s_nop 0
	v_add_f32_e32 v72, v34, v35
	v_mov_b64 v[34:35], v[178:179]
	v_mov_b64 v[36:37], v[180:181]
	v_mov_b64 v[38:39], v[174:175]
	v_mov_b64 v[40:41], v[176:177]
	v_mov_b64 v[42:43], v[170:171]
	v_mov_b64 v[44:45], v[172:173]
	v_mov_b64 v[46:47], v[166:167]
	v_mov_b64 v[48:49], v[168:169]
	v_mov_b64 v[50:51], v[162:163]
	v_mov_b64 v[52:53], v[164:165]
	v_mov_b64 v[54:55], v[158:159]
	v_mov_b64 v[56:57], v[160:161]
	v_mov_b64 v[80:81], v[154:155]
	v_mov_b64 v[82:83], v[156:157]
	v_mov_b64 v[84:85], v[150:151]
	v_mov_b64 v[86:87], v[152:153]
	ds_bpermute_b32 v73, v74, v72
	s_waitcnt lgkmcnt(0)
	v_add_f32_e32 v72, v72, v73
	ds_bpermute_b32 v73, v75, v72
	s_waitcnt lgkmcnt(0)
	v_add_f32_e32 v72, v72, v73
	ds_bpermute_b32 v73, v76, v72
	s_waitcnt lgkmcnt(0)
	v_add_f32_e32 v72, v72, v73
	ds_bpermute_b32 v73, v77, v72
	s_waitcnt lgkmcnt(0)
	v_add_f32_e32 v72, v72, v73
	ds_bpermute_b32 v73, v78, v72
	s_waitcnt lgkmcnt(0)
	v_add_f32_e32 v72, v72, v73
	ds_bpermute_b32 v73, v79, v72
	s_waitcnt lgkmcnt(0)
	v_add_f32_e32 v72, v72, v73
	v_fmamk_f32 v72, v72, 0x3a000000, v221
	v_cmp_gt_f32_e32 vcc, s87, v72
	v_mul_f32_e32 v73, 0x4f800000, v72
	s_nop 0
	v_cndmask_b32_e32 v72, v72, v73, vcc
	v_sqrt_f32_e32 v73, v72
	s_nop 0
	v_add_u32_e32 v74, -1, v73
	v_fma_f32 v75, -v74, v73, v72
	v_cmp_ge_f32_e64 s[0:1], 0, v75
	v_add_u32_e32 v75, 1, v73
	s_nop 0
	v_cndmask_b32_e64 v74, v73, v74, s[0:1]
	v_fma_f32 v73, -v75, v73, v72
	v_cmp_lt_f32_e64 s[0:1], 0, v73
	s_nop 1
	v_cndmask_b32_e64 v73, v74, v75, s[0:1]
	v_mul_f32_e32 v74, 0x37800000, v73
	v_cndmask_b32_e32 v73, v73, v74, vcc
	v_cmp_class_f32_e32 vcc, v72, v222
	s_nop 1
	v_cndmask_b32_e32 v72, v73, v72, vcc
	v_div_scale_f32 v73, s[0:1], v72, v72, 1.0
	v_rcp_f32_e32 v74, v73
	s_brev_b32 s0, 39
	v_fma_f32 v75, -v73, v74, 1.0
	v_fmac_f32_e32 v74, v75, v74
	v_div_scale_f32 v75, vcc, 1.0, v72, 1.0
	v_mul_f32_e32 v76, v75, v74
	v_fma_f32 v77, -v73, v76, v75
	v_fmac_f32_e32 v76, v77, v74
	v_fma_f32 v73, -v73, v76, v75
	v_div_fmas_f32 v73, v73, v74, v76
	v_div_fixup_f32 v72, v73, v72, 1.0
	v_pk_mul_f32 v[6:7], v[6:7], v[72:73] op_sel_hi:[1,0]
	v_pk_mul_f32 v[8:9], v[8:9], v[72:73] op_sel_hi:[1,0]
	v_pk_mul_f32 v[6:7], v[84:85], v[6:7]
	v_pk_mul_f32 v[8:9], v[86:87], v[8:9]
	v_pk_mul_f32 v[2:3], v[2:3], v[72:73] op_sel_hi:[1,0]
	v_pk_mul_f32 v[4:5], v[4:5], v[72:73] op_sel_hi:[1,0]
	v_cvt_pk_bf16_f32 v6, v6, v7
	v_cvt_pk_bf16_f32 v7, v8, v9
	v_add_co_u32_e32 v8, vcc, s0, v68
	v_pk_mul_f32 v[2:3], v[80:81], v[2:3]
	v_pk_mul_f32 v[4:5], v[82:83], v[4:5]
	v_addc_co_u32_e32 v9, vcc, -1, v69, vcc
	v_cvt_pk_bf16_f32 v2, v2, v3
	v_cvt_pk_bf16_f32 v3, v4, v5
	global_store_dwordx2 v[8:9], v[2:3], off offset:-3072
	v_pk_mul_f32 v[2:3], v[10:11], v[72:73] op_sel_hi:[1,0]
	v_pk_mul_f32 v[4:5], v[12:13], v[72:73] op_sel_hi:[1,0]
	v_pk_mul_f32 v[2:3], v[54:55], v[2:3]
	v_pk_mul_f32 v[4:5], v[56:57], v[4:5]
	v_cvt_pk_bf16_f32 v2, v2, v3
	v_cvt_pk_bf16_f32 v3, v4, v5
	global_store_dwordx2 v[8:9], v[2:3], off offset:-2560
	v_pk_mul_f32 v[2:3], v[14:15], v[72:73] op_sel_hi:[1,0]
	v_pk_mul_f32 v[4:5], v[16:17], v[72:73] op_sel_hi:[1,0]
	v_pk_mul_f32 v[2:3], v[50:51], v[2:3]
	v_pk_mul_f32 v[4:5], v[52:53], v[4:5]
	v_cvt_pk_bf16_f32 v2, v2, v3
	v_cvt_pk_bf16_f32 v3, v4, v5
	global_store_dwordx2 v[8:9], v[2:3], off offset:-2048
	v_pk_mul_f32 v[2:3], v[18:19], v[72:73] op_sel_hi:[1,0]
	v_pk_mul_f32 v[4:5], v[20:21], v[72:73] op_sel_hi:[1,0]
	v_pk_mul_f32 v[2:3], v[46:47], v[2:3]
	v_pk_mul_f32 v[4:5], v[48:49], v[4:5]
	v_cvt_pk_bf16_f32 v2, v2, v3
	v_cvt_pk_bf16_f32 v3, v4, v5
	global_store_dwordx2 v[8:9], v[2:3], off offset:-1536
	v_pk_mul_f32 v[2:3], v[22:23], v[72:73] op_sel_hi:[1,0]
	v_pk_mul_f32 v[4:5], v[24:25], v[72:73] op_sel_hi:[1,0]
	v_pk_mul_f32 v[2:3], v[42:43], v[2:3]
	v_pk_mul_f32 v[4:5], v[44:45], v[4:5]
	v_cvt_pk_bf16_f32 v2, v2, v3
	v_cvt_pk_bf16_f32 v3, v4, v5
	global_store_dwordx2 v[8:9], v[2:3], off offset:-1024
	v_pk_mul_f32 v[2:3], v[26:27], v[72:73] op_sel_hi:[1,0]
	v_pk_mul_f32 v[4:5], v[28:29], v[72:73] op_sel_hi:[1,0]
	v_pk_mul_f32 v[2:3], v[38:39], v[2:3]
	v_pk_mul_f32 v[4:5], v[40:41], v[4:5]
	v_cvt_pk_bf16_f32 v2, v2, v3
	v_cvt_pk_bf16_f32 v3, v4, v5
	global_store_dwordx2 v[8:9], v[2:3], off offset:-512
	v_pk_mul_f32 v[2:3], v[30:31], v[72:73] op_sel_hi:[1,0]
	v_pk_mul_f32 v[4:5], v[32:33], v[72:73] op_sel_hi:[1,0]
	v_pk_mul_f32 v[2:3], v[34:35], v[2:3]
	v_pk_mul_f32 v[4:5], v[36:37], v[4:5]
	v_cvt_pk_bf16_f32 v2, v2, v3
	v_cvt_pk_bf16_f32 v3, v4, v5
	global_store_dwordx2 v[8:9], v[6:7], off offset:-3584
	global_store_dwordx2 v[8:9], v[2:3], off
	s_branch .LBB0_87

;     __device__ __forceinline__ const float* in(int i) const { return (const float*)(const __attribute__((address_space(1))) float*)get(i); }
;     __device__ __forceinline__ float* out() const { return (float*)(__attribute__((address_space(1))) float*)get(21); }
; __global__ void __launch_bounds__(512, 2) mega_fwd(Args ka) {
;     ...
;             else if (k == 6) { float* xo = a.out(); const float* xi = (l == 0) ? a.in(0) : xo;
;                 for (int m = gw; m < M; m += ngw) rowpass_row(xi + (size_t)m * DM, (const bf16*)(ws + WS_Y) + (size_t)m * DM, a.in(16) + (size_t)l * DM, a.in(17) + (size_t)l * DM, xo + (size_t)m * DM, H + (size_t)m * DM, lane); }
.LBB0_95:
	s_cmpk_gt_i32 s4, 0x1fff
	s_cbranch_scc1 .LBB0_100
	s_ashr_i32 s5, s4, 31
	s_lshl_b64 s[16:17], s[30:31], 11
	s_lshl_b64 s[8:9], s[4:5], 12
	s_add_u32 s8, s37, s8
	v_lshlrev_b32_e32 v0, 3, v148
	s_addc_u32 s9, s36, s9
	v_lshl_add_u64 v[2:3], s[8:9], 0, v[0:1]
	s_mov_b64 s[8:9], 0x2e000e00
	s_ashr_i32 s7, s6, 31
	v_lshl_add_u64 v[60:61], v[2:3], 0, s[8:9]
	s_lshl_b64 s[8:9], s[6:7], 12
	s_lshl_b64 s[18:19], s[4:5], 13
	s_add_u32 s10, s0, s18
	s_addc_u32 s11, s1, s19
	s_lshl_b64 s[12:13], s[6:7], 13
	s_add_u32 s14, s14, s18
	v_lshlrev_b32_e32 v62, 4, v148
	v_mov_b32_e32 v63, v1
	s_addc_u32 s15, s15, s19
	s_lshl_b64 s[16:17], s[16:17], 2
	v_mov_b32_e32 v2, s73
	ds_read2_b64 v[56:59], v2 offset0:16 offset1:17
	v_lshlrev_b32_e32 v0, 4, v148
	s_waitcnt lgkmcnt(0)
	v_readfirstlane_b32 s0, v56
	v_readfirstlane_b32 s1, v57
	v_readfirstlane_b32 s18, v58
	v_readfirstlane_b32 s19, v59
	s_add_u32 s0, s0, s16
	s_addc_u32 s1, s1, s17
	global_load_dwordx4 v[126:129], v0, s[0:1] offset:1024
	global_load_dwordx4 v[130:133], v0, s[0:1]
	s_cmp_eq_u64 s[18:19], 0
	s_cbranch_scc1 .Lrp6_nogn
	s_add_u32 s0, s18, s16
	s_addc_u32 s1, s19, s17
	global_load_dwordx4 v[150:153], v0, s[0:1]
	global_load_dwordx4 v[154:157], v0, s[0:1] offset:1024
	global_load_dwordx4 v[158:161], v0, s[0:1] offset:2048
	global_load_dwordx4 v[162:165], v0, s[0:1] offset:3072
	s_add_u32 s0, s0, 0x1000
	s_addc_u32 s1, s1, 0
	global_load_dwordx4 v[166:169], v0, s[0:1]
	global_load_dwordx4 v[170:173], v0, s[0:1] offset:1024
	global_load_dwordx4 v[174:177], v0, s[0:1] offset:2048
	global_load_dwordx4 v[178:181], v0, s[0:1] offset:3072
.Lrp6_nogn:
	s_mov_b32 s5, s4
	s_branch .LBB0_98

; __device__ __forceinline__ float bf_lo(unsigned w) { return __uint_as_float(w << 16); }
; __device__ __forceinline__ float bf_hi(unsigned w) { return __uint_as_float(w & 0xffff0000u); }
; __device__ __forceinline__ void rowpass_row(const float* xi, const bf16* y, const float* gp, const float* gn, float* xo, bf16* h, int lane) {
;     const u32x2* yr = (const u32x2*)y + lane; const f32x4* xr = (const f32x4*)xi + lane; const f32x4* gpr = (const f32x4*)gp + lane;
;     u32x2 yw[8]; f32x4 xv[8], gv[8];
; #pragma unroll
;     for (int j = 0; j < 8; ++j) { yw[j] = yr[64 * j]; xv[j] = xr[64 * j]; gv[j] = gpr[64 * j]; }
;     asm volatile("" : "+v"(xv[0]), "+v"(xv[1]), "+v"(xv[2]), "+v"(xv[3]), "+v"(xv[4]), "+v"(xv[5]), "+v"(xv[6]), "+v"(xv[7]));
;     asm volatile("" : "+v"(gv[0]), "+v"(gv[1]), "+v"(gv[2]), "+v"(gv[3]), "+v"(gv[4]), "+v"(gv[5]), "+v"(gv[6]), "+v"(gv[7]));
;     f32x4 v[8]; float s = 0.f;
; #pragma unroll
;     for (int j = 0; j < 8; ++j) { const u32x2 w = yw[j]; v[j].x = bf_lo(w.x); v[j].y = bf_hi(w.x); v[j].z = bf_lo(w.y); v[j].w = bf_hi(w.y); s += (v[j].x * v[j].x + v[j].y * v[j].y) + (v[j].z * v[j].z + v[j].w * v[j].w); }
;     const float r = 1.0f / sqrtf(wave_sum(s) * (1.0f / DM) + 1e-6f);
.LBB0_98:
	global_load_dwordx2 v[64:65], v[60:61], off offset:-3584
	global_load_dwordx2 v[66:67], v[60:61], off offset:-3072
	global_load_dwordx2 v[68:69], v[60:61], off offset:-2560
	global_load_dwordx2 v[70:71], v[60:61], off offset:-2048
	global_load_dwordx2 v[72:73], v[60:61], off offset:-1536
	global_load_dwordx2 v[74:75], v[60:61], off offset:-1024
	global_load_dwordx2 v[76:77], v[60:61], off offset:-512
	global_load_dwordx2 v[78:79], v[60:61], off
	v_mov_b32_e32 v2, s73
	ds_read2_b64 v[56:59], v2 offset0:16 offset1:17
	v_lshl_add_u64 v[6:7], s[14:15], 0, v[62:63]
	v_lshlrev_b32_e32 v0, 4, v148
	v_add_co_u32_e32 v18, vcc, s70, v6
	s_waitcnt lgkmcnt(0)
	v_readfirstlane_b32 s0, v56
	v_readfirstlane_b32 s1, v57
	s_add_u32 s0, s0, s16
	s_addc_u32 s1, s1, s17
	v_addc_co_u32_e32 v19, vcc, 0, v7, vcc
	v_lshl_add_u64 v[34:35], s[0:1], 0, v[0:1]
	v_add_co_u32_e32 v46, vcc, s70, v34
	global_load_dwordx4 v[14:17], v[6:7], off offset:3072
	global_load_dwordx4 v[10:13], v[6:7], off offset:2048
	global_load_dwordx4 v[2:5], v[6:7], off offset:1024
	s_nop 0
	global_load_dwordx4 v[6:9], v[6:7], off
	s_nop 0
	global_load_dwordx4 v[30:33], v[18:19], off offset:3072
	global_load_dwordx4 v[26:29], v[18:19], off offset:2048
	global_load_dwordx4 v[22:25], v[18:19], off offset:1024
	s_nop 0
	global_load_dwordx4 v[18:21], v[18:19], off
	v_addc_co_u32_e32 v47, vcc, 0, v35, vcc
	global_load_dwordx4 v[50:53], v0, s[0:1] offset:3072
	global_load_dwordx4 v[54:57], v0, s[0:1] offset:2048
	global_load_dwordx4 v[34:37], v[46:47], off offset:3072
	global_load_dwordx4 v[38:41], v[46:47], off offset:2048
	global_load_dwordx4 v[42:45], v[46:47], off offset:1024
	s_nop 0
	global_load_dwordx4 v[46:49], v[46:47], off
	v_readfirstlane_b32 s19, v59
	v_readfirstlane_b32 s18, v58
	s_cmp_eq_u64 s[18:19], 0
	s_waitcnt vmcnt(0)
	v_and_b32_e32 v81, 0xffff0000, v64
	v_and_b32_e32 v83, 0xffff0000, v65
	v_lshlrev_b32_e32 v80, 16, v64
	v_lshlrev_b32_e32 v93, 16, v70
	v_lshlrev_b32_e32 v82, 16, v65
	v_and_b32_e32 v87, 0xffff0000, v67
	v_and_b32_e32 v86, 0xffff0000, v66
	v_lshlrev_b32_e32 v88, 16, v68
	v_and_b32_e32 v89, 0xffff0000, v68
	v_mul_f32_e32 v64, v83, v83
	v_mul_f32_e32 v68, v81, v81
	v_mov_b32_e32 v65, v93
	v_lshlrev_b32_e32 v85, 16, v67
	v_lshlrev_b32_e32 v84, 16, v66
	v_lshlrev_b32_e32 v90, 16, v69
	v_and_b32_e32 v91, 0xffff0000, v69
	v_pk_mul_f32 v[66:67], v[86:87], v[86:87]
	v_pk_fma_f32 v[104:105], v[82:83], v[82:83], v[64:65] op_sel_hi:[1,1,0]
	v_pk_fma_f32 v[68:69], v[80:81], v[80:81], v[68:69] op_sel_hi:[1,1,0]
	v_and_b32_e32 v95, 0xffff0000, v70
	v_lshlrev_b32_e32 v96, 16, v71
	v_and_b32_e32 v97, 0xffff0000, v71
	v_lshlrev_b32_e32 v98, 16, v72
	v_and_b32_e32 v100, 0xffff0000, v72
	v_mul_f32_e32 v70, v89, v89
	v_mul_f32_e32 v72, v91, v91
	v_pk_fma_f32 v[66:67], v[84:85], v[84:85], v[66:67]
	v_mov_b32_e32 v92, v68
	v_mov_b32_e32 v64, v104
	v_lshlrev_b32_e32 v99, 16, v73
	v_and_b32_e32 v101, 0xffff0000, v73
	v_mul_f32_e32 v94, v95, v95
	v_mul_f32_e32 v106, v96, v96
	v_mul_f32_e32 v107, v97, v97
	v_pk_fma_f32 v[70:71], v[88:89], v[88:89], v[70:71] op_sel_hi:[1,1,0]
	v_pk_fma_f32 v[72:73], v[90:91], v[90:91], v[72:73] op_sel_hi:[1,1,0]
	v_pk_add_f32 v[68:69], v[68:69], v[104:105]
	v_pk_add_f32 v[66:67], v[66:67], v[66:67] op_sel:[0,1] op_sel_hi:[1,0]
	v_pk_mul_f32 v[64:65], v[92:93], v[64:65]
	v_mov_b32_e32 v71, v106
	v_mov_b32_e32 v73, v107
	v_mov_b32_e32 v67, v94
	v_mov_b32_e32 v69, v65
	v_pk_mul_f32 v[102:103], v[100:101], v[100:101]
	v_pk_add_f32 v[70:71], v[70:71], v[72:73]
	v_pk_add_f32 v[64:65], v[68:69], v[66:67]
	v_pk_fma_f32 v[102:103], v[98:99], v[98:99], v[102:103]
	v_pk_add_f32 v[64:65], v[64:65], v[70:71]
	v_and_b32_e32 v107, 0xffff0000, v75
	v_and_b32_e32 v106, 0xffff0000, v74
	v_pk_add_f32 v[102:103], v[102:103], v[102:103] op_sel:[0,1] op_sel_hi:[1,0]
	v_lshlrev_b32_e32 v105, 16, v75
	v_lshlrev_b32_e32 v104, 16, v74
	v_pk_mul_f32 v[66:67], v[106:107], v[106:107]
	v_lshlrev_b32_e32 v113, 16, v78
	v_pk_add_f32 v[64:65], v[64:65], v[64:65] op_sel:[0,1] op_sel_hi:[1,0]
	v_pk_fma_f32 v[66:67], v[104:105], v[104:105], v[66:67]
	v_and_b32_e32 v115, 0xffff0000, v78
	v_mov_b32_e32 v112, v64
	v_mov_b32_e32 v68, v102
	v_mov_b32_e32 v69, v113
	v_mul_f32_e32 v70, v115, v115
	v_pk_add_f32 v[64:65], v[64:65], v[102:103]
	v_pk_mul_f32 v[68:69], v[112:113], v[68:69]
	v_pk_add_f32 v[66:67], v[66:67], v[66:67] op_sel:[0,1] op_sel_hi:[1,0]
	v_and_b32_e32 v109, 0xffff0000, v76
	v_and_b32_e32 v111, 0xffff0000, v77
	v_mov_b32_e32 v65, v69
	v_mov_b32_e32 v67, v70
	v_lshlrev_b32_e32 v108, 16, v76
	v_lshlrev_b32_e32 v110, 16, v77
	v_lshlrev_b32_e32 v78, 16, v79
	v_and_b32_e32 v79, 0xffff0000, v79
	v_pk_add_f32 v[64:65], v[64:65], v[66:67]
	v_mul_f32_e32 v66, v109, v109
	v_mul_f32_e32 v68, v111, v111
	v_mul_f32_e32 v71, v78, v78
	v_mul_f32_e32 v72, v79, v79
	v_pk_fma_f32 v[66:67], v[108:109], v[108:109], v[66:67] op_sel_hi:[1,1,0]
	v_pk_fma_f32 v[68:69], v[110:111], v[110:111], v[68:69] op_sel_hi:[1,1,0]
	v_mov_b32_e32 v67, v71
	v_mov_b32_e32 v69, v72
	v_pk_add_f32 v[66:67], v[66:67], v[68:69]
	v_mov_b64 v[70:71], v[126:127]
	v_mov_b64 v[72:73], v[128:129]
	v_mov_b64 v[74:75], v[130:131]
	v_mov_b64 v[76:77], v[132:133]
	v_pk_add_f32 v[64:65], v[64:65], v[66:67]
	v_mov_b32_e32 v114, v113
	v_add_f32_e32 v65, v64, v65
	v_and_b32_e32 v64, 64, v220
	v_add_u32_e32 v69, 64, v64
	v_xor_b32_e32 v64, 32, v220
	v_cmp_lt_i32_e32 vcc, v64, v69
	s_nop 0
	v_cndmask_b32_e32 v64, v220, v64, vcc
	v_lshlrev_b32_e32 v64, 2, v64
	ds_bpermute_b32 v66, v64, v65
	s_waitcnt lgkmcnt(0)
	v_add_f32_e32 v66, v65, v66
	v_xor_b32_e32 v65, 16, v220
	v_cmp_lt_i32_e32 vcc, v65, v69
	s_nop 1
	v_cndmask_b32_e32 v65, v220, v65, vcc
	v_lshlrev_b32_e32 v65, 2, v65
	ds_bpermute_b32 v67, v65, v66
	s_waitcnt lgkmcnt(0)
; __device__ __forceinline__ void rowpass_row(const float* xi, const bf16* y, const float* gp, const float* gn, float* xo, bf16* h, int lane) {
;     ...
;     const float r = 1.0f / sqrtf(wave_sum(s) * (1.0f / DM) + 1e-6f);
;     float s2 = 0.f;
; #pragma unroll
;     for (int j = 0; j < 8; ++j) { v[j] = xv[j] + v[j] * r * gv[j]; s2 += (v[j].x * v[j].x + v[j].y * v[j].y) + (v[j].z * v[j].z + v[j].w * v[j].w); }
;     f32x4* xw = (f32x4*)xo + lane;
; #pragma unroll
;     for (int j = 0; j < 8; ++j) xw[64 * j] = v[j];
	v_add_f32_e32 v67, v66, v67
	v_xor_b32_e32 v66, 8, v220
	v_cmp_lt_i32_e32 vcc, v66, v69
	s_nop 1
	v_cndmask_b32_e32 v66, v220, v66, vcc
	v_lshlrev_b32_e32 v66, 2, v66
	ds_bpermute_b32 v68, v66, v67
	s_waitcnt lgkmcnt(0)
	v_add_f32_e32 v68, v67, v68
	v_xor_b32_e32 v67, 4, v220
	v_cmp_lt_i32_e32 vcc, v67, v69
	s_nop 1
	v_cndmask_b32_e32 v67, v220, v67, vcc
	v_lshlrev_b32_e32 v67, 2, v67
	ds_bpermute_b32 v92, v67, v68
	s_waitcnt lgkmcnt(0)
	v_add_f32_e32 v92, v68, v92
	v_xor_b32_e32 v68, 2, v220
	v_cmp_lt_i32_e32 vcc, v68, v69
	s_nop 1
	v_cndmask_b32_e32 v68, v220, v68, vcc
	v_lshlrev_b32_e32 v68, 2, v68
	ds_bpermute_b32 v94, v68, v92
	s_waitcnt lgkmcnt(0)
	v_add_f32_e32 v92, v92, v94
	v_xor_b32_e32 v94, 1, v220
	v_cmp_lt_i32_e32 vcc, v94, v69
	s_nop 1
	v_cndmask_b32_e32 v69, v220, v94, vcc
	v_lshlrev_b32_e32 v69, 2, v69
	ds_bpermute_b32 v94, v69, v92
	s_waitcnt lgkmcnt(0)
	v_add_f32_e32 v92, v92, v94
	v_fmamk_f32 v92, v92, 0x3a000000, v221
	v_mul_f32_e32 v94, 0x4f800000, v92
	v_cmp_gt_f32_e32 vcc, s87, v92
	s_nop 1
	v_cndmask_b32_e32 v92, v92, v94, vcc
	v_sqrt_f32_e32 v94, v92
	s_nop 0
	v_add_u32_e32 v59, -1, v94
	v_fma_f32 v102, -v59, v94, v92
	v_cmp_ge_f32_e64 s[0:1], 0, v102
	v_add_u32_e32 v102, 1, v94
	s_nop 0
	v_cndmask_b32_e64 v59, v94, v59, s[0:1]
	v_fma_f32 v94, -v102, v94, v92
	v_cmp_lt_f32_e64 s[0:1], 0, v94
	s_nop 1
	v_cndmask_b32_e64 v59, v59, v102, s[0:1]
	v_mul_f32_e32 v94, 0x37800000, v59
	v_cndmask_b32_e32 v59, v59, v94, vcc
	v_cmp_class_f32_e32 vcc, v92, v222
	s_nop 1
	v_cndmask_b32_e32 v59, v59, v92, vcc
	v_div_scale_f32 v92, s[0:1], v59, v59, 1.0
	v_rcp_f32_e32 v94, v92
	s_nop 0
	v_fma_f32 v58, -v92, v94, 1.0
	v_fmac_f32_e32 v94, v58, v94
	v_div_scale_f32 v58, vcc, 1.0, v59, 1.0
	v_mul_f32_e32 v102, v58, v94
	v_fma_f32 v103, -v92, v102, v58
	v_fmac_f32_e32 v102, v103, v94
	v_fma_f32 v58, -v92, v102, v58
	v_div_fmas_f32 v58, v58, v94, v102
	v_div_fixup_f32 v58, v58, v59, 1.0
	v_pk_mul_f32 v[80:81], v[58:59], v[80:81] op_sel_hi:[0,1]
	v_pk_fma_f32 v[6:7], v[74:75], v[80:81], v[6:7]
	v_mov_b32_e32 v74, v84
	v_mov_b32_e32 v75, v86
	v_pk_mul_f32 v[74:75], v[58:59], v[74:75] op_sel_hi:[0,1]
	v_pk_fma_f32 v[2:3], v[70:71], v[74:75], v[2:3]
	v_pk_mul_f32 v[70:71], v[58:59], v[88:89] op_sel_hi:[0,1]
	v_mov_b32_e32 v94, v93
	v_pk_fma_f32 v[10:11], v[54:55], v[70:71], v[10:11]
	v_pk_mul_f32 v[54:55], v[94:95], v[58:59] op_sel_hi:[1,0]
	v_pk_mul_f32 v[82:83], v[58:59], v[82:83] op_sel_hi:[0,1]
	v_mov_b32_e32 v86, v85
	v_pk_fma_f32 v[14:15], v[50:51], v[54:55], v[14:15]
	v_mov_b32_e32 v50, v98
	v_mov_b32_e32 v51, v100
	v_pk_fma_f32 v[8:9], v[76:77], v[82:83], v[8:9]
	v_pk_mul_f32 v[76:77], v[58:59], v[86:87] op_sel_hi:[0,1]
	v_pk_mul_f32 v[50:51], v[58:59], v[50:51] op_sel_hi:[0,1]
	v_pk_fma_f32 v[4:5], v[72:73], v[76:77], v[4:5]
	v_pk_mul_f32 v[72:73], v[58:59], v[90:91] op_sel_hi:[0,1]
	v_pk_fma_f32 v[18:19], v[46:47], v[50:51], v[18:19]
	v_mov_b32_e32 v46, v104
	v_mov_b32_e32 v47, v106
	v_pk_fma_f32 v[12:13], v[56:57], v[72:73], v[12:13]
	v_pk_mul_f32 v[56:57], v[96:97], v[58:59] op_sel_hi:[1,0]
	v_mov_b32_e32 v100, v99
	v_pk_mul_f32 v[46:47], v[58:59], v[46:47] op_sel_hi:[0,1]
	v_pk_fma_f32 v[16:17], v[52:53], v[56:57], v[16:17]
	v_pk_mul_f32 v[52:53], v[58:59], v[100:101] op_sel_hi:[0,1]
	v_mov_b32_e32 v106, v105
	v_pk_fma_f32 v[22:23], v[42:43], v[46:47], v[22:23]
	v_pk_mul_f32 v[42:43], v[58:59], v[108:109] op_sel_hi:[0,1]
	v_pk_fma_f32 v[20:21], v[48:49], v[52:53], v[20:21]
	v_pk_mul_f32 v[48:49], v[58:59], v[106:107] op_sel_hi:[0,1]
	v_pk_fma_f32 v[26:27], v[38:39], v[42:43], v[26:27]
	v_pk_mul_f32 v[38:39], v[114:115], v[58:59] op_sel_hi:[1,0]
	v_pk_fma_f32 v[24:25], v[44:45], v[48:49], v[24:25]
	v_pk_mul_f32 v[44:45], v[58:59], v[110:111] op_sel_hi:[0,1]
	v_pk_fma_f32 v[30:31], v[34:35], v[38:39], v[30:31]
	v_lshl_add_u64 v[34:35], s[10:11], 0, v[62:63]
	v_pk_fma_f32 v[28:29], v[40:41], v[44:45], v[28:29]
	v_pk_mul_f32 v[40:41], v[78:79], v[58:59] op_sel_hi:[1,0]
	global_store_dwordx4 v[34:35], v[6:9], off
	global_store_dwordx4 v[34:35], v[2:5], off offset:1024
	global_store_dwordx4 v[34:35], v[10:13], off offset:2048
	global_store_dwordx4 v[34:35], v[14:17], off offset:3072
	v_add_co_u32_e32 v34, vcc, 0x1000, v34
	v_pk_fma_f32 v[32:33], v[36:37], v[40:41], v[32:33]
	s_nop 0
	v_addc_co_u32_e32 v35, vcc, 0, v35, vcc
	global_store_dwordx4 v[34:35], v[18:21], off
	global_store_dwordx4 v[34:35], v[22:25], off offset:1024
	global_store_dwordx4 v[34:35], v[26:29], off offset:2048
	global_store_dwordx4 v[34:35], v[30:33], off offset:3072
	s_cbranch_scc1 .LBB0_97
; __device__ __forceinline__ unsigned pkh(float lo, float hi) { f32v2_t v; v.x = lo; v.y = hi; return __builtin_bit_cast(unsigned, __builtin_convertvector(v, bf16v2_t)); }
; __device__ __forceinline__ void rowpass_row(const float* xi, const bf16* y, const float* gp, const float* gn, float* xo, bf16* h, int lane) {
;     ...
;     for (int j = 0; j < 8; ++j) { v[j] = xv[j] + v[j] * r * gv[j]; s2 += (v[j].x * v[j].x + v[j].y * v[j].y) + (v[j].z * v[j].z + v[j].w * v[j].w); }
;     f32x4* xw = (f32x4*)xo + lane;
; #pragma unroll
;     for (int j = 0; j < 8; ++j) xw[64 * j] = v[j];
;     if (gn) {
;         const f32x4* gnr = (const f32x4*)gn + lane;
; #pragma unroll
;         for (int j = 0; j < 8; ++j) gv[j] = gnr[64 * j];
;         asm volatile("" : "+v"(gv[0]), "+v"(gv[1]), "+v"(gv[2]), "+v"(gv[3]), "+v"(gv[4]), "+v"(gv[5]), "+v"(gv[6]), "+v"(gv[7]));
;         const float r2 = 1.0f / sqrtf(wave_sum(s2) * (1.0f / DM) + 1e-6f);
;         u32x2* o8 = (u32x2*)h + lane;
; #pragma unroll
;         for (int j = 0; j < 8; ++j) { const f32x4 g = gv[j]; u32x2 w; w.x = pkh(v[j].x * r2 * g.x, v[j].y * r2 * g.y); w.y = pkh(v[j].z * r2 * g.z, v[j].w * r2 * g.w); o8[64 * j] = w; }
	v_mov_b32_e32 v36, v7
	v_mov_b32_e32 v37, v3
	v_mov_b32_e32 v34, v6
	v_mov_b32_e32 v35, v2
	v_pk_mul_f32 v[36:37], v[36:37], v[36:37]
	v_mov_b32_e32 v38, v9
	v_mov_b32_e32 v39, v5
	v_pk_fma_f32 v[34:35], v[34:35], v[34:35], v[36:37]
	v_mov_b32_e32 v36, v8
	v_mov_b32_e32 v37, v4
	v_pk_mul_f32 v[38:39], v[38:39], v[38:39]
	s_add_u32 s0, s18, s16
	v_pk_fma_f32 v[36:37], v[36:37], v[36:37], v[38:39]
	v_pk_mul_f32 v[38:39], v[10:11], v[10:11]
	v_pk_add_f32 v[34:35], v[34:35], v[36:37]
	v_pk_mul_f32 v[36:37], v[12:13], v[12:13]
	v_pk_add_f32 v[34:35], v[34:35], v[34:35] op_sel_hi:[0,1]
	v_pk_mov_b32 v[40:41], v[38:39], v[36:37] op_sel:[1,0]
	v_mov_b32_e32 v39, v37
	v_mul_f32_e32 v34, v14, v14
	v_pk_add_f32 v[36:37], v[40:41], v[38:39]
	v_pk_fma_f32 v[38:39], v[14:15], v[14:15], v[34:35] op_sel_hi:[1,1,0]
	v_mul_f32_e32 v34, v16, v16
	v_pk_add_f32 v[36:37], v[36:37], v[36:37] op_sel_hi:[0,1]
	v_pk_fma_f32 v[40:41], v[16:17], v[16:17], v[34:35] op_sel_hi:[1,1,0]
	v_mul_f32_e32 v38, v18, v18
	v_mul_f32_e32 v40, v19, v19
	v_mul_f32_e32 v36, v20, v20
	v_mul_f32_e32 v34, v21, v21
	v_pk_add_f32 v[38:39], v[38:39], v[40:41]
	v_pk_add_f32 v[34:35], v[36:37], v[34:35]
	v_pk_mul_f32 v[36:37], v[24:25], v[24:25]
	v_pk_add_f32 v[34:35], v[38:39], v[34:35]
	v_pk_mul_f32 v[38:39], v[22:23], v[22:23]
	v_pk_add_f32 v[34:35], v[34:35], v[34:35] op_sel_hi:[0,1]
	v_pk_mov_b32 v[40:41], v[38:39], v[36:37] op_sel:[1,0]
	v_mov_b32_e32 v39, v37
	v_mul_f32_e32 v34, v26, v26
	v_pk_add_f32 v[36:37], v[40:41], v[38:39]
	v_pk_fma_f32 v[38:39], v[26:27], v[26:27], v[34:35] op_sel_hi:[1,1,0]
	v_mul_f32_e32 v34, v28, v28
	v_pk_add_f32 v[36:37], v[36:37], v[36:37] op_sel_hi:[0,1]
	v_pk_fma_f32 v[40:41], v[28:29], v[28:29], v[34:35] op_sel_hi:[1,1,0]
	v_mul_f32_e32 v38, v30, v30
	v_mul_f32_e32 v40, v31, v31
	v_mul_f32_e32 v36, v32, v32
	v_mul_f32_e32 v34, v33, v33
	v_pk_add_f32 v[38:39], v[38:39], v[40:41]
	v_pk_add_f32 v[34:35], v[36:37], v[34:35]
	s_addc_u32 s1, s19, s17
	v_pk_add_f32 v[34:35], v[38:39], v[34:35]
	s_nop 0
	v_add_f32_e32 v58, v34, v35
	v_lshl_add_u64 v[34:35], s[0:1], 0, v[0:1]
	v_add_co_u32_e32 v46, vcc, s70, v34
	s_nop 1
	v_addc_co_u32_e32 v47, vcc, 0, v35, vcc
	v_mov_b64 v[34:35], v[178:179]
	v_mov_b64 v[36:37], v[180:181]
	v_mov_b64 v[38:39], v[174:175]
	v_mov_b64 v[40:41], v[176:177]
	v_mov_b64 v[42:43], v[170:171]
	v_mov_b64 v[44:45], v[172:173]
	v_mov_b64 v[46:47], v[166:167]
	v_mov_b64 v[48:49], v[168:169]
	v_mov_b64 v[50:51], v[162:163]
	v_mov_b64 v[52:53], v[164:165]
	v_mov_b64 v[54:55], v[158:159]
	v_mov_b64 v[56:57], v[160:161]
	v_mov_b64 v[70:71], v[154:155]
	v_mov_b64 v[72:73], v[156:157]
	v_mov_b64 v[74:75], v[150:151]
	v_mov_b64 v[76:77], v[152:153]
	ds_bpermute_b32 v0, v64, v58
	s_waitcnt lgkmcnt(0)
	v_add_f32_e32 v0, v58, v0
	ds_bpermute_b32 v58, v65, v0
	s_waitcnt lgkmcnt(0)
	v_add_f32_e32 v0, v0, v58
	ds_bpermute_b32 v58, v66, v0
	s_waitcnt lgkmcnt(0)
	v_add_f32_e32 v0, v0, v58
	ds_bpermute_b32 v58, v67, v0
	s_waitcnt lgkmcnt(0)
	v_add_f32_e32 v0, v0, v58
	ds_bpermute_b32 v58, v68, v0
	s_waitcnt lgkmcnt(0)
	v_add_f32_e32 v0, v0, v58
	ds_bpermute_b32 v58, v69, v0
	s_waitcnt lgkmcnt(0)
	v_add_f32_e32 v0, v0, v58
	v_fmamk_f32 v0, v0, 0x3a000000, v221
	v_cmp_gt_f32_e32 vcc, s87, v0
	v_mul_f32_e32 v58, 0x4f800000, v0
	s_nop 0
	v_cndmask_b32_e32 v0, v0, v58, vcc
	v_sqrt_f32_e32 v58, v0
	s_nop 0
	v_add_u32_e32 v59, -1, v58
	v_fma_f32 v64, -v59, v58, v0
	v_cmp_ge_f32_e64 s[0:1], 0, v64
	v_add_u32_e32 v64, 1, v58
	s_nop 0
	v_cndmask_b32_e64 v59, v58, v59, s[0:1]
	v_fma_f32 v58, -v64, v58, v0
	v_cmp_lt_f32_e64 s[0:1], 0, v58
	s_nop 1
	v_cndmask_b32_e64 v58, v59, v64, s[0:1]
	v_mul_f32_e32 v59, 0x37800000, v58
	v_cndmask_b32_e32 v58, v58, v59, vcc
	v_cmp_class_f32_e32 vcc, v0, v222
	s_nop 1
	v_cndmask_b32_e32 v0, v58, v0, vcc
	v_div_scale_f32 v58, s[0:1], v0, v0, 1.0
	v_rcp_f32_e32 v59, v58
	s_brev_b32 s0, 39
	v_fma_f32 v64, -v58, v59, 1.0
	v_fmac_f32_e32 v59, v64, v59
	v_div_scale_f32 v64, vcc, 1.0, v0, 1.0
	v_mul_f32_e32 v65, v64, v59
	v_fma_f32 v66, -v58, v65, v64
	v_fmac_f32_e32 v65, v66, v59
	v_fma_f32 v58, -v58, v65, v64
	v_div_fmas_f32 v58, v58, v59, v65
	v_div_fixup_f32 v0, v58, v0, 1.0
	v_pk_mul_f32 v[6:7], v[6:7], v[0:1] op_sel_hi:[1,0]
	v_pk_mul_f32 v[8:9], v[8:9], v[0:1] op_sel_hi:[1,0]
	v_pk_mul_f32 v[6:7], v[74:75], v[6:7]
	v_pk_mul_f32 v[8:9], v[76:77], v[8:9]
	v_pk_mul_f32 v[2:3], v[2:3], v[0:1] op_sel_hi:[1,0]
	v_pk_mul_f32 v[4:5], v[4:5], v[0:1] op_sel_hi:[1,0]
	v_cvt_pk_bf16_f32 v6, v6, v7
	v_cvt_pk_bf16_f32 v7, v8, v9
	v_add_co_u32_e32 v8, vcc, s0, v60
	v_pk_mul_f32 v[2:3], v[70:71], v[2:3]
	v_pk_mul_f32 v[4:5], v[72:73], v[4:5]
	v_addc_co_u32_e32 v9, vcc, -1, v61, vcc
	v_cvt_pk_bf16_f32 v2, v2, v3
	v_cvt_pk_bf16_f32 v3, v4, v5
	global_store_dwordx2 v[8:9], v[2:3], off offset:-3072
	v_pk_mul_f32 v[2:3], v[10:11], v[0:1] op_sel_hi:[1,0]
	v_pk_mul_f32 v[4:5], v[12:13], v[0:1] op_sel_hi:[1,0]
	v_pk_mul_f32 v[2:3], v[54:55], v[2:3]
	v_pk_mul_f32 v[4:5], v[56:57], v[4:5]
	v_cvt_pk_bf16_f32 v2, v2, v3
	v_cvt_pk_bf16_f32 v3, v4, v5
	global_store_dwordx2 v[8:9], v[2:3], off offset:-2560
	v_pk_mul_f32 v[2:3], v[14:15], v[0:1] op_sel_hi:[1,0]
	v_pk_mul_f32 v[4:5], v[16:17], v[0:1] op_sel_hi:[1,0]
	v_pk_mul_f32 v[2:3], v[50:51], v[2:3]
	v_pk_mul_f32 v[4:5], v[52:53], v[4:5]
	v_cvt_pk_bf16_f32 v2, v2, v3
	v_cvt_pk_bf16_f32 v3, v4, v5
	global_store_dwordx2 v[8:9], v[2:3], off offset:-2048
	v_pk_mul_f32 v[2:3], v[18:19], v[0:1] op_sel_hi:[1,0]
	v_pk_mul_f32 v[4:5], v[20:21], v[0:1] op_sel_hi:[1,0]
	v_pk_mul_f32 v[2:3], v[46:47], v[2:3]
	v_pk_mul_f32 v[4:5], v[48:49], v[4:5]
	v_cvt_pk_bf16_f32 v2, v2, v3
	v_cvt_pk_bf16_f32 v3, v4, v5
	global_store_dwordx2 v[8:9], v[2:3], off offset:-1536
	v_pk_mul_f32 v[2:3], v[22:23], v[0:1] op_sel_hi:[1,0]
	v_pk_mul_f32 v[4:5], v[24:25], v[0:1] op_sel_hi:[1,0]
	v_pk_mul_f32 v[2:3], v[42:43], v[2:3]
	v_pk_mul_f32 v[4:5], v[44:45], v[4:5]
	v_cvt_pk_bf16_f32 v2, v2, v3
	v_cvt_pk_bf16_f32 v3, v4, v5
	global_store_dwordx2 v[8:9], v[2:3], off offset:-1024
	v_pk_mul_f32 v[2:3], v[26:27], v[0:1] op_sel_hi:[1,0]
	v_pk_mul_f32 v[4:5], v[28:29], v[0:1] op_sel_hi:[1,0]
	v_pk_mul_f32 v[2:3], v[38:39], v[2:3]
	v_pk_mul_f32 v[4:5], v[40:41], v[4:5]
	v_cvt_pk_bf16_f32 v2, v2, v3
	v_cvt_pk_bf16_f32 v3, v4, v5
	global_store_dwordx2 v[8:9], v[2:3], off offset:-512
	v_pk_mul_f32 v[2:3], v[30:31], v[0:1] op_sel_hi:[1,0]
	v_pk_mul_f32 v[4:5], v[32:33], v[0:1] op_sel_hi:[1,0]
	v_pk_mul_f32 v[2:3], v[34:35], v[2:3]
	v_pk_mul_f32 v[4:5], v[36:37], v[4:5]
	v_cvt_pk_bf16_f32 v2, v2, v3
	v_cvt_pk_bf16_f32 v3, v4, v5
	global_store_dwordx2 v[8:9], v[6:7], off offset:-3584
	global_store_dwordx2 v[8:9], v[2:3], off
	s_branch .LBB0_97
